# grid barrier: non-leader workgroups poll the top-level generation word directly (one hop fewer per seam)
# baseline (speedup 1.0000x reference)
.LBB0_106:
	s_or_b64 exec, exec, s[14:15]
	v_cvt_f32_u32_e32 v4, v2
	s_waitcnt vmcnt(0)
	v_readfirstlane_b32 s3, v3
	v_sub_u32_e32 v3, 0, v2
	v_rcp_iflag_f32_e32 v4, v4
	v_add_u32_e32 v5, s3, v1
	v_mul_f32_e32 v4, 0x4f7ffffe, v4
	v_cvt_u32_f32_e32 v4, v4
	v_mul_lo_u32 v1, v3, v4
	v_mul_hi_u32 v1, v4, v1
	v_add_u32_e32 v1, v4, v1
	v_mul_hi_u32 v1, v5, v1
	v_mul_lo_u32 v3, v1, v2
	v_sub_u32_e32 v3, v5, v3
	v_add_u32_e32 v4, 1, v1
	v_cmp_ge_u32_e32 vcc, v3, v2
	s_nop 1
	v_cndmask_b32_e32 v1, v1, v4, vcc
	v_sub_u32_e32 v4, v3, v2
	v_cndmask_b32_e32 v3, v3, v4, vcc
	v_add_u32_e32 v4, 1, v1
	v_cmp_ge_u32_e32 vcc, v3, v2
	v_add_u32_e32 v3, 1, v5
	s_nop 0
	v_cndmask_b32_e32 v1, v1, v4, vcc
	v_mul_lo_u32 v4, v2, v1
	v_add_u32_e32 v2, v4, v2
	v_cmp_ne_u32_e32 vcc, v3, v2
	s_and_saveexec_b64 s[12:13], vcc
	s_xor_b64 s[12:13], exec, s[12:13]
	s_cbranch_execz .LBB0_120
	s_waitcnt lgkmcnt(0)
	v_mov_b32_e32 v0, 0x3500
	global_load_dword v0, v0, s[48:49] sc1
	s_add_u32 s18, s48, 0x3500
	s_addc_u32 s19, s49, 0
	s_waitcnt vmcnt(0)
	v_cmp_eq_u32_e32 vcc, v0, v1
	s_and_saveexec_b64 s[14:15], vcc
	s_cbranch_execz .LBB0_119
	s_add_u32 s16, s28, 0x30300200
	s_addc_u32 s17, s29, 0
	s_mov_b32 s3, 1
	s_mov_b64 s[20:21], 0
	v_mov_b32_e32 v0, 0
	s_branch .LBB0_110

.LBB0_2418:
	s_or_b64 exec, exec, s[12:13]
	v_cvt_f32_u32_e32 v4, v2
	s_waitcnt vmcnt(0)
	v_readfirstlane_b32 s3, v3
	v_sub_u32_e32 v3, 0, v2
	v_rcp_iflag_f32_e32 v4, v4
	v_add_u32_e32 v5, s3, v1
	v_mul_f32_e32 v4, 0x4f7ffffe, v4
	v_cvt_u32_f32_e32 v4, v4
	v_mul_lo_u32 v1, v3, v4
	v_mul_hi_u32 v1, v4, v1
	v_add_u32_e32 v1, v4, v1
	v_mul_hi_u32 v1, v5, v1
	v_mul_lo_u32 v3, v1, v2
	v_sub_u32_e32 v3, v5, v3
	v_add_u32_e32 v4, 1, v1
	v_cmp_ge_u32_e32 vcc, v3, v2
	s_nop 1
	v_cndmask_b32_e32 v1, v1, v4, vcc
	v_sub_u32_e32 v4, v3, v2
	v_cndmask_b32_e32 v3, v3, v4, vcc
	v_add_u32_e32 v4, 1, v1
	v_cmp_ge_u32_e32 vcc, v3, v2
	v_add_u32_e32 v3, 1, v5
	s_nop 0
	v_cndmask_b32_e32 v1, v1, v4, vcc
	v_mul_lo_u32 v4, v2, v1
	v_add_u32_e32 v2, v4, v2
	v_cmp_ne_u32_e32 vcc, v3, v2
	s_and_saveexec_b64 s[10:11], vcc
	s_xor_b64 s[10:11], exec, s[10:11]
	s_cbranch_execz .LBB0_2432
	s_waitcnt lgkmcnt(0)
	v_mov_b32_e32 v0, 0x3500
	global_load_dword v0, v0, s[48:49] sc1
	s_add_u32 s16, s48, 0x3500
	s_addc_u32 s17, s49, 0
	s_waitcnt vmcnt(0)
	v_cmp_eq_u32_e32 vcc, v0, v1
	s_and_saveexec_b64 s[12:13], vcc
	s_cbranch_execz .LBB0_2431
	s_add_u32 s14, s28, 0x30300200
	s_addc_u32 s15, s29, 0
	s_mov_b32 s3, 1
	s_mov_b64 s[18:19], 0
	v_mov_b32_e32 v0, 0
	s_branch .LBB0_2422
